# NA attention bias/mask block de-serialised (16 ds_read2_b32 gathers in flight + 4 VALU per score); MLA loop with 2-tile-deep double-staged prefetch
# speedup vs baseline: 1.0500x; 1.0113x over previous
.LBB0_1041:
	s_and_b64 vcc, exec, s[8:9]
	v_mov_b32_e32 v1, 0xf149f2ca
	s_cbranch_vccnz .LBB0_1108
	s_cmp_lt_u32 s29, 3
	s_cbranch_scc1 .LBB0_1109
	v_med3_i32 v2, v189, 8, 56
	v_add_u32_e32 v2, -8, v2
	v_sub_u32_e32 v2, v2, v146
	v_sub_u32_e32 v3, v146, v189
	s_add_i32 s8, s26, 0xb22c
	v_lshl_add_u32 v3, v3, 2, s8
	ds_read2_b32 v[64:65], v3 offset0:0 offset1:1
	ds_read2_b32 v[66:67], v3 offset0:2 offset1:3
	ds_read2_b32 v[68:69], v3 offset0:8 offset1:9
	ds_read2_b32 v[70:71], v3 offset0:10 offset1:11
	ds_read2_b32 v[72:73], v3 offset0:16 offset1:17
	ds_read2_b32 v[74:75], v3 offset0:18 offset1:19
	ds_read2_b32 v[76:77], v3 offset0:24 offset1:25
	ds_read2_b32 v[78:79], v3 offset0:26 offset1:27
	ds_read2_b32 v[48:49], v3 offset0:32 offset1:33
	ds_read2_b32 v[50:51], v3 offset0:34 offset1:35
	ds_read2_b32 v[52:53], v3 offset0:40 offset1:41
	ds_read2_b32 v[54:55], v3 offset0:42 offset1:43
	v_sub_u32_e32 v149, 0, v2
	s_waitcnt lgkmcnt(11)
	v_cmp_gt_u32_e32 vcc, 16, v149
	v_add_f32_e32 v64, v96, v64
	v_sub_u32_e32 v150, 1, v2
	v_cndmask_b32_e32 v64, v1, v64, vcc
	v_cmp_gt_u32_e32 vcc, 16, v150
	v_add_f32_e32 v65, v97, v65
	v_sub_u32_e32 v149, 2, v2
	v_cndmask_b32_e32 v65, v1, v65, vcc
	ds_read2_b32 v[56:57], v3 offset0:48 offset1:49
	s_waitcnt lgkmcnt(11)
	v_cmp_gt_u32_e32 vcc, 16, v149
	v_add_f32_e32 v66, v98, v66
	v_sub_u32_e32 v150, 3, v2
	v_cndmask_b32_e32 v66, v1, v66, vcc
	v_cmp_gt_u32_e32 vcc, 16, v150
	v_add_f32_e32 v67, v99, v67
	v_sub_u32_e32 v149, 8, v2
	v_cndmask_b32_e32 v67, v1, v67, vcc
	ds_read2_b32 v[58:59], v3 offset0:50 offset1:51
	s_waitcnt lgkmcnt(11)
	v_cmp_gt_u32_e32 vcc, 16, v149
	v_add_f32_e32 v68, v100, v68
	v_sub_u32_e32 v150, 9, v2
	v_cndmask_b32_e32 v68, v1, v68, vcc
	v_cmp_gt_u32_e32 vcc, 16, v150
	v_add_f32_e32 v69, v101, v69
	v_sub_u32_e32 v149, 10, v2
	v_cndmask_b32_e32 v69, v1, v69, vcc
	ds_read2_b32 v[60:61], v3 offset0:56 offset1:57
	s_waitcnt lgkmcnt(11)
	v_cmp_gt_u32_e32 vcc, 16, v149
	v_add_f32_e32 v70, v102, v70
	v_sub_u32_e32 v150, 11, v2
	v_cndmask_b32_e32 v70, v1, v70, vcc
	v_cmp_gt_u32_e32 vcc, 16, v150
	v_add_f32_e32 v71, v103, v71
	v_sub_u32_e32 v149, 16, v2
	v_cndmask_b32_e32 v71, v1, v71, vcc
	ds_read2_b32 v[62:63], v3 offset0:58 offset1:59
	s_waitcnt lgkmcnt(11)
	v_cmp_gt_u32_e32 vcc, 16, v149
	v_add_f32_e32 v72, v104, v72
	v_sub_u32_e32 v150, 17, v2
	v_cndmask_b32_e32 v72, v1, v72, vcc
	v_cmp_gt_u32_e32 vcc, 16, v150
	v_add_f32_e32 v73, v105, v73
	v_sub_u32_e32 v149, 18, v2
	v_cndmask_b32_e32 v73, v1, v73, vcc
	s_waitcnt lgkmcnt(10)
	v_cmp_gt_u32_e32 vcc, 16, v149
	v_add_f32_e32 v74, v106, v74
	v_sub_u32_e32 v150, 19, v2
	v_cndmask_b32_e32 v74, v1, v74, vcc
	v_cmp_gt_u32_e32 vcc, 16, v150
	v_add_f32_e32 v75, v107, v75
	v_sub_u32_e32 v149, 24, v2
	v_cndmask_b32_e32 v75, v1, v75, vcc
	s_waitcnt lgkmcnt(9)
	v_cmp_gt_u32_e32 vcc, 16, v149
	v_add_f32_e32 v76, v108, v76
	v_sub_u32_e32 v150, 25, v2
	v_cndmask_b32_e32 v76, v1, v76, vcc
	v_cmp_gt_u32_e32 vcc, 16, v150
	v_add_f32_e32 v77, v109, v77
	v_sub_u32_e32 v149, 26, v2
	v_cndmask_b32_e32 v77, v1, v77, vcc
	s_waitcnt lgkmcnt(8)
	v_cmp_gt_u32_e32 vcc, 16, v149
	v_add_f32_e32 v78, v110, v78
	v_sub_u32_e32 v150, 27, v2
	v_cndmask_b32_e32 v78, v1, v78, vcc
	v_cmp_gt_u32_e32 vcc, 16, v150
	v_add_f32_e32 v79, v111, v79
	v_sub_u32_e32 v149, 32, v2
	v_cndmask_b32_e32 v79, v1, v79, vcc
	s_waitcnt lgkmcnt(7)
	v_cmp_gt_u32_e32 vcc, 16, v149
	v_add_f32_e32 v48, v80, v48
	v_sub_u32_e32 v150, 33, v2
	v_cndmask_b32_e32 v48, v1, v48, vcc
	v_cmp_gt_u32_e32 vcc, 16, v150
	v_add_f32_e32 v49, v81, v49
	v_sub_u32_e32 v149, 34, v2
	v_cndmask_b32_e32 v49, v1, v49, vcc
	s_waitcnt lgkmcnt(6)
	v_cmp_gt_u32_e32 vcc, 16, v149
	v_add_f32_e32 v50, v82, v50
	v_sub_u32_e32 v150, 35, v2
	v_cndmask_b32_e32 v50, v1, v50, vcc
	v_cmp_gt_u32_e32 vcc, 16, v150
	v_add_f32_e32 v51, v83, v51
	v_sub_u32_e32 v149, 40, v2
	v_cndmask_b32_e32 v51, v1, v51, vcc
	s_waitcnt lgkmcnt(5)
	v_cmp_gt_u32_e32 vcc, 16, v149
	v_add_f32_e32 v52, v84, v52
	v_sub_u32_e32 v150, 41, v2
	v_cndmask_b32_e32 v52, v1, v52, vcc
	v_cmp_gt_u32_e32 vcc, 16, v150
	v_add_f32_e32 v53, v85, v53
	v_sub_u32_e32 v149, 42, v2
	v_cndmask_b32_e32 v53, v1, v53, vcc
	s_waitcnt lgkmcnt(4)
	v_cmp_gt_u32_e32 vcc, 16, v149
	v_add_f32_e32 v54, v86, v54
	v_sub_u32_e32 v150, 43, v2
	v_cndmask_b32_e32 v54, v1, v54, vcc
	v_cmp_gt_u32_e32 vcc, 16, v150
	v_add_f32_e32 v55, v87, v55
	v_sub_u32_e32 v149, 48, v2
	v_cndmask_b32_e32 v55, v1, v55, vcc
	s_waitcnt lgkmcnt(3)
	v_cmp_gt_u32_e32 vcc, 16, v149
	v_add_f32_e32 v56, v88, v56
	v_sub_u32_e32 v150, 49, v2
	v_cndmask_b32_e32 v56, v1, v56, vcc
	v_cmp_gt_u32_e32 vcc, 16, v150
	v_add_f32_e32 v57, v89, v57
	v_sub_u32_e32 v149, 50, v2
	v_cndmask_b32_e32 v57, v1, v57, vcc
	s_waitcnt lgkmcnt(2)
	v_cmp_gt_u32_e32 vcc, 16, v149
	v_add_f32_e32 v58, v90, v58
	v_sub_u32_e32 v150, 51, v2
	v_cndmask_b32_e32 v58, v1, v58, vcc
	v_cmp_gt_u32_e32 vcc, 16, v150
	v_add_f32_e32 v59, v91, v59
	v_sub_u32_e32 v149, 56, v2
	v_cndmask_b32_e32 v59, v1, v59, vcc
	s_waitcnt lgkmcnt(1)
	v_cmp_gt_u32_e32 vcc, 16, v149
	v_add_f32_e32 v60, v92, v60
	v_sub_u32_e32 v150, 57, v2
	v_cndmask_b32_e32 v60, v1, v60, vcc
	v_cmp_gt_u32_e32 vcc, 16, v150
	v_add_f32_e32 v61, v93, v61
	v_sub_u32_e32 v149, 58, v2
	v_cndmask_b32_e32 v61, v1, v61, vcc
	s_waitcnt lgkmcnt(0)
	v_cmp_gt_u32_e32 vcc, 16, v149
	v_add_f32_e32 v62, v94, v62
	v_sub_u32_e32 v150, 59, v2
	v_cndmask_b32_e32 v62, v1, v62, vcc
	v_cmp_gt_u32_e32 vcc, 16, v150
	v_add_f32_e32 v63, v95, v63
	s_nop 0
	v_cndmask_b32_e32 v63, v1, v63, vcc
	s_branch .LBB0_1110

; #define LOADK(t) do { const int kp_ = TILE_KPOS(t); kreg = *(const u32x4*)((const char*)P.K + (size_t)(koff + (unsigned)(kp_ * KPITCH * 2))); if (VAR == 0 && tid < 256) pereg = *(const u32x4*)((const char*)P.KPE + (size_t)(peoff + (unsigned)(kp_ * 64))); } while (0)
; #define LOADV(t) do { const int kp_ = TILE_KPOS(t); vreg = *(const u32x4*)((const char*)P.VT + (size_t)(voff + (unsigned)(kp_ * 2))); } while (0)
; #define STOREK(buf) do { LAS unsigned char* kb_ = lds + (buf) * ABUF; *(LAS u32x4*)(kb_ + (tid >> 3) * KP + (tid & 7) * 16) = kreg; \
;         if (VAR == 0 && tid < 256) *(LAS u32x4*)(kb_ + (tid >> 2) * KP + 128 + (tid & 3) * 16) = pereg; } while (0)
; #define STOREV(buf) do { *(LAS u32x4*)(lds + (buf) * ABUF + KT_BYTES + (tid >> 3) * VP + (tid & 7) * 16) = vreg; } while (0)
; template <int VAR>
; __device__ __forceinline__ void attn_phase(LAS unsigned char* lds, const AttnP P, int vcu, int G, int wave_s) {
;     ...
;         const int rot = (VAR == 0 && !isctx) ? ((vcu & 31) * 4 + (vcu >> 5)) % 132 : 0;
;         int na_rs = 0; if (VAR == 2) { na_rs = p_b - 4; na_rs = na_rs < 0 ? 0 : (na_rs > 120 ? 120 : na_rs); }
;         LOADK(0); LOADV(0); STOREK(0); STOREV(0);
;         if (nt > 1) { LOADK(1); STOREK(1); }
;         __syncthreads();
;         f32x16 pc0, pc1; const f32x16 zero16 = {};
;         QK_TILE(pc0, pc1, 0, zero16);
;         float mref = rowmax32(pc0, pc1), lrun = 0.f;
;         if (VAR == 1) { const float sk = P.sink[hq] * LOG2E; mref = __builtin_fmaxf(mref, sk); lrun = (hi == 0) ? __builtin_amdgcn_exp2f(sk - mref) : 0.f; }
;         f32x16 negm = {};
;         if (USE_NEGM) {
; #pragma unroll
;             for (int r = 0; r < 16; ++r) { pc0[r] -= mref; pc1[r] -= mref; negm[r] = -mref; }
;         }
;         float rmc = 0.f;
;         bool need_c = true;
;         __syncthreads();
;         for (int t = 0; t < nt; ++t) {
;             const bool hn = (t + 1 < nt);
;             if (hn) { const int t2 = (t + 2 < nt) ? t + 2 : nt - 1; LOADK(t2); LOADV(t + 1); }
.LBB0_1173:
	s_or_b64 exec, exec, s[0:1]
	s_waitcnt vmcnt(0)
	ds_write_b128 v172, v[2:5] offset:22528
	s_and_saveexec_b64 s[0:1], s[2:3]
	ds_write_b128 v176, v[138:141] offset:22656
	s_or_b64 exec, exec, s[0:1]
	s_waitcnt lgkmcnt(0)
	s_barrier
	ds_read_b128 v[2:5], v174
	ds_read_b128 v[6:9], v174 offset:32
	s_waitcnt lgkmcnt(1)
	v_mfma_f32_32x32x16_bf16 v[34:49], v[2:5], v[114:117], 0
	ds_read_b128 v[2:5], v174 offset:6656
	ds_read_b128 v[10:13], v174 offset:6688
	v_readlane_b32 s36, v255, 18
	s_mov_b32 s0, s36
	v_readlane_b32 s37, v255, 19
	v_readlane_b32 s38, v255, 20
	v_readlane_b32 s39, v255, 21
	v_readlane_b32 s40, v255, 22
	s_waitcnt lgkmcnt(2)
	v_mfma_f32_32x32x16_bf16 v[34:49], v[6:9], v[118:121], v[34:49]
	v_readlane_b32 s41, v255, 23
	v_readlane_b32 s42, v255, 24
	v_readlane_b32 s43, v255, 25
	v_readlane_b32 s44, v255, 26
	v_readlane_b32 s45, v255, 27
	v_readlane_b32 s46, v255, 28
	v_readlane_b32 s47, v255, 29
	s_waitcnt lgkmcnt(1)
	v_mfma_f32_32x32x16_bf16 v[18:33], v[2:5], v[114:117], 0
	ds_read_b128 v[2:5], v174 offset:64
	ds_read_b128 v[6:9], v174 offset:96
	v_readlane_b32 s48, v255, 30
	v_readlane_b32 s49, v255, 31
	v_readlane_b32 s50, v255, 32
	v_readlane_b32 s51, v255, 33
	v_writelane_b32 v255, s0, 18
	s_mov_b32 s37, s36
	s_waitcnt lgkmcnt(1)
	v_mfma_f32_32x32x16_bf16 v[34:49], v[2:5], v[122:125], v[34:49]
	v_writelane_b32 v255, s1, 19
	v_writelane_b32 v255, s2, 20
	v_writelane_b32 v255, s3, 21
	v_writelane_b32 v255, s4, 22
	v_writelane_b32 v255, s5, 23
	v_writelane_b32 v255, s6, 24
	v_writelane_b32 v255, s7, 25
	v_mfma_f32_32x32x16_bf16 v[18:33], v[10:13], v[118:121], v[18:33]
	ds_read_b128 v[2:5], v174 offset:6720
	ds_read_b128 v[10:13], v174 offset:6752
	v_writelane_b32 v255, s8, 26
	v_writelane_b32 v255, s9, 27
	v_writelane_b32 v255, s10, 28
	v_writelane_b32 v255, s11, 29
	v_writelane_b32 v255, s12, 30
	v_writelane_b32 v255, s13, 31
	s_waitcnt lgkmcnt(2)
	v_mfma_f32_32x32x16_bf16 v[34:49], v[6:9], v[126:129], v[34:49]
	v_writelane_b32 v255, s14, 32
	s_mov_b32 s38, s36
	s_mov_b32 s39, s36
	s_mov_b32 s40, s36
	s_mov_b32 s41, s36
	s_mov_b32 s42, s36
	s_mov_b32 s43, s36
	s_waitcnt lgkmcnt(1)
	v_mfma_f32_32x32x16_bf16 v[18:33], v[2:5], v[122:125], v[18:33]
	ds_read_b128 v[2:5], v174 offset:128
	ds_read_b128 v[6:9], v174 offset:160
	ds_read_b128 v[50:53], v174 offset:6816
	s_mov_b32 s44, s36
	s_mov_b32 s45, s36
	s_mov_b32 s46, s36
	s_mov_b32 s47, s36
	s_mov_b32 s48, s36
	s_waitcnt lgkmcnt(2)
	v_mfma_f32_32x32x16_bf16 v[34:49], v[2:5], v[130:133], v[34:49]
	ds_read_b128 v[2:5], v174 offset:6784
	s_mov_b32 s49, s36
	s_mov_b32 s50, s36
	s_mov_b32 s51, s36
	v_writelane_b32 v255, s15, 33
	s_movk_i32 s0, 0x4200
	v_mul_lo_u32 v1, v1, s0
	v_mfma_f32_32x32x16_bf16 v[18:33], v[10:13], v[126:129], v[18:33]
	v_or_b32_e32 v1, v171, v1
	s_add_i32 s12, s9, -1
	v_lshl_add_u32 v181, s10, 7, v1
	v_mov_b32_e32 v1, 0
	s_mov_b32 s11, 1
	v_mov_b32_e32 v82, 0
	s_waitcnt lgkmcnt(0)
	v_mfma_f32_32x32x16_bf16 v[18:33], v[2:5], v[130:133], v[18:33]
	s_barrier
	v_mfma_f32_32x32x16_bf16 v[34:49], v[6:9], v[134:137], v[34:49]
	v_mov_b64_e32 v[2:3], s[36:37]
	v_mov_b64_e32 v[16:17], s[50:51]
	v_mov_b64_e32 v[4:5], s[38:39]
	v_mov_b64_e32 v[6:7], s[40:41]
	v_mov_b64_e32 v[8:9], s[42:43]
	v_mov_b64_e32 v[10:11], s[44:45]
	v_mov_b64_e32 v[12:13], s[46:47]
	v_mfma_f32_32x32x16_bf16 v[18:33], v[50:53], v[134:137], v[18:33]
	s_nop 3
	v_max_f32_e32 v54, v35, v35
	v_max_f32_e32 v55, v34, v34
	v_max_f32_e32 v54, v55, v54
	v_mov_b64_e32 v[14:15], s[48:49]
	s_nop 3
	v_max3_f32 v50, v36, v37, v19
	v_max3_f32 v51, v54, v18, v20
	v_max3_f32 v51, v51, v21, v38
	v_max3_f32 v50, v50, v40, v41
	v_max3_f32 v51, v51, v39, v22
	v_max3_f32 v50, v50, v24, v25
	v_max3_f32 v51, v51, v23, v42
	v_max3_f32 v50, v50, v44, v45
	v_max3_f32 v51, v51, v43, v26
	v_max3_f32 v50, v50, v28, v29
	v_max3_f32 v51, v51, v27, v46
	v_max3_f32 v50, v50, v48, v49
	v_max3_f32 v51, v51, v47, v30
	v_max3_f32 v50, v50, v32, v33
	v_max3_f32 v50, v51, v31, v50
	v_mov_b32_e32 v51, v50
	s_nop 1
	v_permlane32_swap_b32_e32 v50, v51
	v_max_f32_e32 v51, v51, v51
	v_max_f32_e32 v50, v50, v50
	v_max_f32_e32 v180, v50, v51
	v_xor_b32_e32 v66, 0x80000000, v180
	v_sub_f32_e32 v65, v33, v180
	v_sub_f32_e32 v64, v32, v180
	v_sub_f32_e32 v63, v31, v180
	v_sub_f32_e32 v62, v30, v180
	v_sub_f32_e32 v61, v29, v180
	v_sub_f32_e32 v60, v28, v180
	v_sub_f32_e32 v59, v27, v180
	v_sub_f32_e32 v58, v26, v180
	v_sub_f32_e32 v57, v25, v180
	v_sub_f32_e32 v56, v24, v180
	v_sub_f32_e32 v55, v23, v180
	v_sub_f32_e32 v54, v22, v180
	v_sub_f32_e32 v53, v21, v180
	v_sub_f32_e32 v52, v20, v180
	v_sub_f32_e32 v51, v19, v180
	v_sub_f32_e32 v50, v18, v180
	v_mov_b64_e32 v[32:33], v[16:17]
	v_sub_f32_e32 v49, v49, v180
	v_sub_f32_e32 v48, v48, v180
	v_sub_f32_e32 v47, v47, v180
	v_sub_f32_e32 v46, v46, v180
	v_sub_f32_e32 v45, v45, v180
	v_sub_f32_e32 v44, v44, v180
	v_sub_f32_e32 v43, v43, v180
	v_sub_f32_e32 v42, v42, v180
	v_sub_f32_e32 v41, v41, v180
	v_sub_f32_e32 v40, v40, v180
	v_sub_f32_e32 v39, v39, v180
	v_sub_f32_e32 v38, v38, v180
	v_sub_f32_e32 v37, v37, v180
	v_sub_f32_e32 v36, v36, v180
	v_sub_f32_e32 v35, v35, v180
	v_sub_f32_e32 v34, v34, v180
	v_mov_b64_e32 v[30:31], v[14:15]
	v_mov_b64_e32 v[28:29], v[12:13]
	v_mov_b64_e32 v[26:27], v[10:11]
	v_mov_b64_e32 v[24:25], v[8:9]
	v_mov_b64_e32 v[22:23], v[6:7]
	v_mov_b64_e32 v[20:21], v[4:5]
	v_mov_b64_e32 v[18:19], v[2:3]
	v_mov_b32_e32 v67, v66
	v_mov_b32_e32 v68, v66
	v_mov_b32_e32 v69, v66
	v_mov_b32_e32 v70, v66
	v_mov_b32_e32 v71, v66
	v_mov_b32_e32 v72, v66
	v_mov_b32_e32 v73, v66
	v_mov_b32_e32 v74, v66
	v_mov_b32_e32 v75, v66
	v_mov_b32_e32 v76, v66
	v_mov_b32_e32 v77, v66
	v_mov_b32_e32 v78, v66
	v_mov_b32_e32 v79, v66
	v_mov_b32_e32 v80, v66
	v_mov_b32_e32 v81, v66
	v_add_u32_e32 v228, v166, v165
	v_mov_b32_e32 v167, v82
	s_add_i32 s0, s10, 1
	s_lshl_b32 s0, s0, 7
	v_subrev_u32_e32 v168, s0, v181
	s_add_i32 s0, s11, 1
	s_min_u32 s0, s0, s12
	s_add_i32 s0, s0, s10
	s_cmp_ge_i32 s0, s9
	s_cselect_b32 s1, s9, 0
	s_sub_i32 s19, s0, s1
	s_add_i32 s0, s11, 0
	s_min_u32 s0, s0, s12
	s_add_i32 s0, s0, s10
	s_cmp_ge_i32 s0, s9
	s_cselect_b32 s1, s9, 0
	s_sub_i32 s13, s0, s1
	s_and_saveexec_b64 s[0:1], s[2:3]
	s_cbranch_execz .Lmla_pre0
	v_lshl_add_u32 v229, s19, 12, v179
	global_load_dwordx4 v[138:141], v229, s[62:63]
; #define LAS __attribute__((address_space(3)))
; template <int VAR>
; __device__ __forceinline__ void attn_phase(LAS unsigned char* lds, const AttnP P, int vcu, int G, int wave_s) {
;     ...
;             if (hn) { const int t2 = (t + 2 < nt) ? t + 2 : nt - 1; LOADK(t2); LOADV(t + 1); }
;             const bool need_n = hn && NEED(t + 1);
;             if (need_c && __any(rmc > THR)) {
;                 const float dl = __builtin_fmaxf(rmc, 0.f), f = __builtin_amdgcn_exp2f(-dl);
;                 mref += dl; lrun *= f;
; #pragma unroll
;                 for (int r = 0; r < 16; ++r) { if (USE_NEGM) { pc0[r] -= dl; pc1[r] -= dl; negm[r] = -mref; } o0[r] *= f; o1[r] *= f; }
;             }
;             f32x16 pn0 = {}, pn1 = {};
;             float rmn = -1e30f;
;             if (VAR != 2 && need_c && need_n) {
;                 const LAS unsigned char* kt_ = lds + ((t + 1) & 1) * ABUF; const LAS unsigned char* vt_ = lds + (t & 1) * ABUF + KT_BYTES;
;                 bf16x8 kf[2 * ND0], vf[8]; u32x4 w0, w1, w2, w3; float sacc = 0.f;
;     ...
;                 if (ND0 == 6) {
;                     KR1(0); KR1(1); KR1(2); KR1(3); SB();
;                     QK1(0, negm); EX2(pc0, 0, w0.x); KR1(4); SB();
;                     QK1(1, negm); EX2(pc0, 2, w0.y); KR1(5); SB();
;                     QK1(2, pn0); EX2(pc0, 4, w0.z); KR1(6); SB();
;                     QK1(3, pn1); EX2(pc0, 6, w0.w); KR1(7); SB();
;                     QK1(4, pn0); EX2(pc0, 8, w1.x); KR1(8); SB();
;                     QK1(5, pn1); EX2(pc0, 10, w1.y); KR1(9); SB();
;                     QK1(6, pn0); EX2(pc0, 12, w1.z); KR1(10); SB();
;                     QK1(7, pn1); EX2(pc0, 14, w1.w); KR1(11); SB();
;                     QK1(8, pn0); EX2(pc1, 0, w2.x); VR1(0); SB();
;                     QK1(9, pn1); EX2(pc1, 2, w2.y); VR1(1); SB();
;                     QK1(10, pn0); EX2(pc1, 4, w2.z); VR1(2); SB();
;                     QK1(11, pn1); EX2(pc1, 6, w2.w); VR1(3); SB();
;                 } else {
;                     KR1(0); KR1(1); KR1(2); KR1(3); SB();
;                     QK1(0, negm); EX2(pc0, 0, w0.x); EX2(pc0, 2, w0.y); KR1(4); SB();
;                     QK1(1, negm); EX2(pc0, 4, w0.z); EX2(pc0, 6, w0.w); KR1(5); SB();
;                     QK1(2, pn0); EX2(pc0, 8, w1.x); EX2(pc0, 10, w1.y); KR1(6); SB();
;                     QK1(3, pn1); EX2(pc0, 12, w1.z); EX2(pc0, 14, w1.w); KR1(7); SB();
.Lmla_pre0:
	s_or_b64 exec, exec, s[0:1]
	v_lshl_add_u32 v229, s19, 17, v178
	global_load_dwordx4 v[146:149], v229, s[52:53]
	v_lshl_add_u32 v229, s13, 7, v168
	global_load_dwordx4 v[142:145], v229, s[56:57]
	s_add_i32 s0, s11, 2
	s_min_u32 s0, s0, s12
	s_add_i32 s0, s0, s10
	s_cmp_ge_i32 s0, s9
	s_cselect_b32 s1, s9, 0
	s_sub_i32 s19, s0, s1
	s_add_i32 s0, s11, 1
	s_min_u32 s0, s0, s12
	s_add_i32 s0, s0, s10
	s_cmp_ge_i32 s0, s9
	s_cselect_b32 s1, s9, 0
	s_sub_i32 s13, s0, s1
	s_and_saveexec_b64 s[0:1], s[2:3]
	s_cbranch_execz .Lmla_pre1
	v_lshl_add_u32 v229, s19, 12, v179
	global_load_dwordx4 v[160:163], v229, s[62:63]
.Lmla_pre1:
	s_or_b64 exec, exec, s[0:1]
	v_lshl_add_u32 v229, s19, 17, v178
	global_load_dwordx4 v[150:153], v229, s[52:53]
	v_lshl_add_u32 v229, s13, 7, v168
	global_load_dwordx4 v[202:205], v229, s[56:57]
.Lmla_A:
	ds_read_b128 v[182:185], v174 offset:22528
	ds_read_b128 v[186:189], v174 offset:29184
	ds_read_b128 v[190:193], v174 offset:22560
	ds_read_b128 v[194:197], v174 offset:29216
	v_cmp_lt_f32_e32 vcc, s66, v167
	s_cbranch_vccnz .Lmla_A_resc
.Lmla_A_go:
	v_exp_f32_e32 v222, v34
	v_exp_f32_e32 v223, v35
	v_add_f32_e32 v164, 0, v222
	v_cvt_pk_bf16_f32 v206, v222, v223
	v_add_f32_e32 v164, v223, v164
	v_exp_f32_e32 v224, v36
	v_exp_f32_e32 v225, v37
	v_add_f32_e32 v164, v224, v164
	v_cvt_pk_bf16_f32 v207, v224, v225
	v_add_f32_e32 v164, v225, v164
	s_waitcnt lgkmcnt(3)
	v_mfma_f32_32x32x16_bf16 v[82:97], v[182:185], v[114:117], v[66:81]
	ds_read_b128 v[198:201], v174 offset:22592
	v_exp_f32_e32 v222, v38
	v_exp_f32_e32 v223, v39
	v_add_f32_e32 v164, v222, v164
	v_cvt_pk_bf16_f32 v208, v222, v223
	v_add_f32_e32 v164, v223, v164
	s_waitcnt lgkmcnt(3)
	v_mfma_f32_32x32x16_bf16 v[98:113], v[186:189], v[114:117], v[66:81]
	ds_read_b128 v[182:185], v174 offset:29248
	v_exp_f32_e32 v224, v40
	v_exp_f32_e32 v225, v41
	v_add_f32_e32 v164, v224, v164
	v_cvt_pk_bf16_f32 v209, v224, v225
	v_add_f32_e32 v164, v225, v164
	s_waitcnt lgkmcnt(3)
	v_mfma_f32_32x32x16_bf16 v[82:97], v[190:193], v[118:121], v[82:97]
	ds_read_b128 v[186:189], v174 offset:22624
	v_exp_f32_e32 v222, v42
	v_exp_f32_e32 v223, v43
	v_add_f32_e32 v164, v222, v164
	v_cvt_pk_bf16_f32 v210, v222, v223
	v_add_f32_e32 v164, v223, v164
	s_waitcnt lgkmcnt(3)
	v_mfma_f32_32x32x16_bf16 v[98:113], v[194:197], v[118:121], v[98:113]
	ds_read_b128 v[190:193], v174 offset:29280
	v_exp_f32_e32 v224, v44
	v_exp_f32_e32 v225, v45
	v_add_f32_e32 v164, v224, v164
	v_cvt_pk_bf16_f32 v211, v224, v225
	v_add_f32_e32 v164, v225, v164
	s_waitcnt lgkmcnt(3)
	v_mfma_f32_32x32x16_bf16 v[82:97], v[198:201], v[122:125], v[82:97]
	ds_read_b128 v[194:197], v174 offset:22656
	v_exp_f32_e32 v222, v46
	v_exp_f32_e32 v223, v47
	v_add_f32_e32 v164, v222, v164
	v_cvt_pk_bf16_f32 v212, v222, v223
	v_add_f32_e32 v164, v223, v164
	s_waitcnt lgkmcnt(3)
	v_mfma_f32_32x32x16_bf16 v[98:113], v[182:185], v[122:125], v[98:113]
	ds_read_b128 v[198:201], v174 offset:29312
	v_exp_f32_e32 v224, v48
	v_exp_f32_e32 v225, v49
	v_add_f32_e32 v164, v224, v164
	v_cvt_pk_bf16_f32 v213, v224, v225
	v_add_f32_e32 v164, v225, v164
	s_waitcnt lgkmcnt(3)
	v_mfma_f32_32x32x16_bf16 v[82:97], v[186:189], v[126:129], v[82:97]
	ds_read_b128 v[182:185], v174 offset:22688
	v_exp_f32_e32 v222, v50
	v_exp_f32_e32 v223, v51
	v_add_f32_e32 v164, v222, v164
	v_cvt_pk_bf16_f32 v214, v222, v223
	v_add_f32_e32 v164, v223, v164
	s_waitcnt lgkmcnt(3)
	v_mfma_f32_32x32x16_bf16 v[98:113], v[190:193], v[126:129], v[98:113]
	ds_read_b128 v[186:189], v174 offset:29344
	v_exp_f32_e32 v224, v52
	v_exp_f32_e32 v225, v53
	v_add_f32_e32 v164, v224, v164
	v_cvt_pk_bf16_f32 v215, v224, v225
	v_add_f32_e32 v164, v225, v164
	s_waitcnt lgkmcnt(3)
	v_mfma_f32_32x32x16_bf16 v[82:97], v[194:197], v[130:133], v[82:97]
	ds_read_b128 v[190:193], v228 offset:13312
	v_exp_f32_e32 v222, v54
	v_exp_f32_e32 v223, v55
	v_add_f32_e32 v164, v222, v164
	v_cvt_pk_bf16_f32 v216, v222, v223
	v_add_f32_e32 v164, v223, v164
	s_waitcnt lgkmcnt(3)
	v_mfma_f32_32x32x16_bf16 v[98:113], v[198:201], v[130:133], v[98:113]
	ds_read_b128 v[194:197], v228 offset:17920
	v_exp_f32_e32 v224, v56
	v_exp_f32_e32 v225, v57
	v_add_f32_e32 v164, v224, v164
	v_cvt_pk_bf16_f32 v217, v224, v225
	v_add_f32_e32 v164, v225, v164
	s_waitcnt lgkmcnt(3)
	v_mfma_f32_32x32x16_bf16 v[82:97], v[182:185], v[134:137], v[82:97]
	ds_read_b128 v[198:201], v228 offset:13344
	v_exp_f32_e32 v222, v58
	v_exp_f32_e32 v223, v59
	v_add_f32_e32 v164, v222, v164
	v_cvt_pk_bf16_f32 v218, v222, v223
	v_add_f32_e32 v164, v223, v164
	s_waitcnt lgkmcnt(3)
	v_mfma_f32_32x32x16_bf16 v[98:113], v[186:189], v[134:137], v[98:113]
	ds_read_b128 v[182:185], v228 offset:17952
	v_exp_f32_e32 v224, v60
	v_exp_f32_e32 v225, v61
	v_add_f32_e32 v164, v224, v164
	v_cvt_pk_bf16_f32 v219, v224, v225
	v_add_f32_e32 v164, v225, v164
	s_waitcnt lgkmcnt(3)
	v_mfma_f32_32x32x16_bf16 v[2:17], v[190:193], v[206:209], v[2:17]
	ds_read_b128 v[186:189], v228 offset:13376
	v_exp_f32_e32 v222, v62
	v_exp_f32_e32 v223, v63
	v_add_f32_e32 v164, v222, v164
	v_cvt_pk_bf16_f32 v220, v222, v223
	v_add_f32_e32 v164, v223, v164
	s_waitcnt lgkmcnt(3)
	v_mfma_f32_32x32x16_bf16 v[18:33], v[194:197], v[206:209], v[18:33]
	ds_read_b128 v[190:193], v228 offset:17984
	v_exp_f32_e32 v224, v64
	v_exp_f32_e32 v225, v65
	v_add_f32_e32 v164, v224, v164
	v_cvt_pk_bf16_f32 v221, v224, v225
	v_add_f32_e32 v164, v225, v164
	s_waitcnt lgkmcnt(3)
	v_mfma_f32_32x32x16_bf16 v[2:17], v[198:201], v[210:213], v[2:17]
	ds_read_b128 v[194:197], v228 offset:13408
	v_max3_f32 v224, v82, v83, v84
	v_max3_f32 v225, v98, v99, v100
	v_max3_f32 v224, v224, v85, v86
	s_waitcnt lgkmcnt(3)
	v_mfma_f32_32x32x16_bf16 v[18:33], v[182:185], v[210:213], v[18:33]
	ds_read_b128 v[198:201], v228 offset:18016
	v_max3_f32 v225, v225, v101, v102
	v_max3_f32 v224, v224, v87, v88
	v_max3_f32 v225, v225, v103, v104
	s_waitcnt lgkmcnt(3)
	v_mfma_f32_32x32x16_bf16 v[2:17], v[186:189], v[214:217], v[2:17]
	v_max3_f32 v224, v224, v89, v90
	v_max3_f32 v225, v225, v105, v106
	v_max3_f32 v224, v224, v91, v92
	s_add_i32 s0, s11, 3
	s_min_u32 s0, s0, s12
	s_add_i32 s0, s0, s10
	s_cmp_ge_i32 s0, s9
	s_cselect_b32 s1, s9, 0
	s_sub_i32 s19, s0, s1
	s_add_i32 s0, s11, 2
	s_min_u32 s0, s0, s12
	s_add_i32 s0, s0, s10
	s_cmp_ge_i32 s0, s9
	s_cselect_b32 s1, s9, 0
	s_sub_i32 s13, s0, s1
	s_waitcnt lgkmcnt(2)
	v_mfma_f32_32x32x16_bf16 v[18:33], v[190:193], v[214:217], v[18:33]
	v_max3_f32 v225, v225, v107, v108
	v_max3_f32 v224, v224, v93, v94
	v_max3_f32 v225, v225, v109, v110
	s_and_b64 vcc, exec, s[2:3]
	s_cbranch_vccz .Lmla_A_w47
	s_waitcnt vmcnt(3)
	ds_write_b128 v176, v[138:141] offset:128
	ds_write_b128 v172, v[146:149]
	ds_write_b128 v173, v[142:145] offset:35840
	v_lshl_add_u32 v229, s19, 12, v179
	global_load_dwordx4 v[138:141], v229, s[62:63]
	v_lshl_add_u32 v229, s19, 17, v178
	global_load_dwordx4 v[146:149], v229, s[52:53]
	v_lshl_add_u32 v229, s13, 7, v168
	global_load_dwordx4 v[142:145], v229, s[56:57]
	s_branch .Lmla_A_join
; template <int VAR>
; __device__ __forceinline__ void attn_phase(LAS unsigned char* lds, const AttnP P, int vcu, int G, int wave_s) {
;     ...
;                 if (ND0 == 6) {
;                     KR1(0); KR1(1); KR1(2); KR1(3); SB();
;                     QK1(0, negm); EX2(pc0, 0, w0.x); KR1(4); SB();
;                     QK1(1, negm); EX2(pc0, 2, w0.y); KR1(5); SB();
;                     QK1(2, pn0); EX2(pc0, 4, w0.z); KR1(6); SB();
;                     QK1(3, pn1); EX2(pc0, 6, w0.w); KR1(7); SB();
;                     QK1(4, pn0); EX2(pc0, 8, w1.x); KR1(8); SB();
;                     QK1(5, pn1); EX2(pc0, 10, w1.y); KR1(9); SB();
;                     QK1(6, pn0); EX2(pc0, 12, w1.z); KR1(10); SB();
;                     QK1(7, pn1); EX2(pc0, 14, w1.w); KR1(11); SB();
;                     QK1(8, pn0); EX2(pc1, 0, w2.x); VR1(0); SB();
;                     QK1(9, pn1); EX2(pc1, 2, w2.y); VR1(1); SB();
;                     QK1(10, pn0); EX2(pc1, 4, w2.z); VR1(2); SB();
;                     QK1(11, pn1); EX2(pc1, 6, w2.w); VR1(3); SB();
;                 } else {
;                     KR1(0); KR1(1); KR1(2); KR1(3); SB();
;                     QK1(0, negm); EX2(pc0, 0, w0.x); EX2(pc0, 2, w0.y); KR1(4); SB();
;                     QK1(1, negm); EX2(pc0, 4, w0.z); EX2(pc0, 6, w0.w); KR1(5); SB();
;                     QK1(2, pn0); EX2(pc0, 8, w1.x); EX2(pc0, 10, w1.y); KR1(6); SB();
;                     QK1(3, pn1); EX2(pc0, 12, w1.z); EX2(pc0, 14, w1.w); KR1(7); SB();
;                     QK1(4, pn0); EX2(pc1, 0, w2.x); VR1(0); SB();
;                     QK1(5, pn1); EX2(pc1, 2, w2.y); VR1(1); SB();
;                     QK1(6, pn0); EX2(pc1, 4, w2.z); VR1(2); SB();
;                     QK1(7, pn1); EX2(pc1, 6, w2.w); VR1(3); SB();
;                 }
;                 PV1(0, w0); EX2(pc1, 8, w3.x); VR1(4); SB();
;                 PV1(1, w0); EX2(pc1, 10, w3.y); VR1(5); SB();
;                 PV1(2, w1); EX2(pc1, 12, w3.z); VR1(6); SB();
;                 PV1(3, w1); EX2(pc1, 14, w3.w); VR1(7); SB();
;                 lrun += sacc;
;                 PV1(4, w2); MASK_TILE(pn0, pn1, t + 1); SB();
;                 PV1(5, w2); SB();
;                 PV1(6, w3); SB();
;                 PV1(7, w3); rmn = rowmax32(pn0, pn1); if (!USE_NEGM) rmn -= mref; SB();
;     ...
;             if (hn) { STOREK(t & 1); STOREV((t + 1) & 1); }
;             __syncthreads();
.Lmla_A_w47:
	s_waitcnt vmcnt(2)
	ds_write_b128 v172, v[146:149]
	ds_write_b128 v173, v[142:145] offset:35840
	v_lshl_add_u32 v229, s19, 17, v178
	global_load_dwordx4 v[146:149], v229, s[52:53]
	v_lshl_add_u32 v229, s13, 7, v168
	global_load_dwordx4 v[142:145], v229, s[56:57]
.Lmla_A_join:
	s_waitcnt lgkmcnt(3)
	v_mfma_f32_32x32x16_bf16 v[2:17], v[194:197], v[218:221], v[2:17]
	v_max3_f32 v224, v224, v95, v96
	v_max3_f32 v225, v225, v111, v112
	s_waitcnt lgkmcnt(2)
	v_mfma_f32_32x32x16_bf16 v[18:33], v[198:201], v[218:221], v[18:33]
	v_max3_f32 v224, v224, v97, v113
	v_max_f32_e32 v224, v224, v225
	v_mov_b32_e32 v225, v224
	v_add_f32_e32 v1, v1, v164
	s_add_i32 s11, s11, 1
	s_nop 0
	v_permlane32_swap_b32_e32 v224, v225
	s_cmp_eq_u32 s9, s11
	v_max_f32_e32 v167, v224, v225
	s_waitcnt lgkmcnt(0)
	s_barrier
	s_cbranch_scc1 .Lmla_exit_A
.Lmla_B:
	ds_read_b128 v[182:185], v174
	ds_read_b128 v[186:189], v174 offset:6656
	ds_read_b128 v[190:193], v174 offset:32
	ds_read_b128 v[194:197], v174 offset:6688
	v_cmp_lt_f32_e32 vcc, s66, v167
	s_cbranch_vccnz .Lmla_B_resc
.Lmla_B_go:
	v_exp_f32_e32 v222, v82
	v_exp_f32_e32 v223, v83
	v_add_f32_e32 v164, 0, v222
	v_cvt_pk_bf16_f32 v206, v222, v223
	v_add_f32_e32 v164, v223, v164
	v_exp_f32_e32 v224, v84
	v_exp_f32_e32 v225, v85
	v_add_f32_e32 v164, v224, v164
	v_cvt_pk_bf16_f32 v207, v224, v225
	v_add_f32_e32 v164, v225, v164
	s_waitcnt lgkmcnt(3)
	v_mfma_f32_32x32x16_bf16 v[34:49], v[182:185], v[114:117], v[66:81]
	ds_read_b128 v[198:201], v174 offset:64
	v_exp_f32_e32 v222, v86
	v_exp_f32_e32 v223, v87
	v_add_f32_e32 v164, v222, v164
	v_cvt_pk_bf16_f32 v208, v222, v223
	v_add_f32_e32 v164, v223, v164
	s_waitcnt lgkmcnt(3)
	v_mfma_f32_32x32x16_bf16 v[50:65], v[186:189], v[114:117], v[66:81]
	ds_read_b128 v[182:185], v174 offset:6720
	v_exp_f32_e32 v224, v88
	v_exp_f32_e32 v225, v89
	v_add_f32_e32 v164, v224, v164
	v_cvt_pk_bf16_f32 v209, v224, v225
	v_add_f32_e32 v164, v225, v164
	s_waitcnt lgkmcnt(3)
	v_mfma_f32_32x32x16_bf16 v[34:49], v[190:193], v[118:121], v[34:49]
	ds_read_b128 v[186:189], v174 offset:96
	v_exp_f32_e32 v222, v90
	v_exp_f32_e32 v223, v91
	v_add_f32_e32 v164, v222, v164
	v_cvt_pk_bf16_f32 v210, v222, v223
	v_add_f32_e32 v164, v223, v164
	s_waitcnt lgkmcnt(3)
	v_mfma_f32_32x32x16_bf16 v[50:65], v[194:197], v[118:121], v[50:65]
	ds_read_b128 v[190:193], v174 offset:6752
	v_exp_f32_e32 v224, v92
	v_exp_f32_e32 v225, v93
	v_add_f32_e32 v164, v224, v164
	v_cvt_pk_bf16_f32 v211, v224, v225
	v_add_f32_e32 v164, v225, v164
	s_waitcnt lgkmcnt(3)
	v_mfma_f32_32x32x16_bf16 v[34:49], v[198:201], v[122:125], v[34:49]
	ds_read_b128 v[194:197], v174 offset:128
	v_exp_f32_e32 v222, v94
	v_exp_f32_e32 v223, v95
	v_add_f32_e32 v164, v222, v164
	v_cvt_pk_bf16_f32 v212, v222, v223
	v_add_f32_e32 v164, v223, v164
	s_waitcnt lgkmcnt(3)
	v_mfma_f32_32x32x16_bf16 v[50:65], v[182:185], v[122:125], v[50:65]
	ds_read_b128 v[198:201], v174 offset:6784
	v_exp_f32_e32 v224, v96
	v_exp_f32_e32 v225, v97
	v_add_f32_e32 v164, v224, v164
	v_cvt_pk_bf16_f32 v213, v224, v225
	v_add_f32_e32 v164, v225, v164
	s_waitcnt lgkmcnt(3)
	v_mfma_f32_32x32x16_bf16 v[34:49], v[186:189], v[126:129], v[34:49]
	ds_read_b128 v[182:185], v174 offset:160
	v_exp_f32_e32 v222, v98
	v_exp_f32_e32 v223, v99
	v_add_f32_e32 v164, v222, v164
	v_cvt_pk_bf16_f32 v214, v222, v223
	v_add_f32_e32 v164, v223, v164
	s_waitcnt lgkmcnt(3)
	v_mfma_f32_32x32x16_bf16 v[50:65], v[190:193], v[126:129], v[50:65]
	ds_read_b128 v[186:189], v174 offset:6816
	v_exp_f32_e32 v224, v100
	v_exp_f32_e32 v225, v101
	v_add_f32_e32 v164, v224, v164
	v_cvt_pk_bf16_f32 v215, v224, v225
	v_add_f32_e32 v164, v225, v164
	s_waitcnt lgkmcnt(3)
	v_mfma_f32_32x32x16_bf16 v[34:49], v[194:197], v[130:133], v[34:49]
	ds_read_b128 v[190:193], v228 offset:35840
	v_exp_f32_e32 v222, v102
	v_exp_f32_e32 v223, v103
	v_add_f32_e32 v164, v222, v164
	v_cvt_pk_bf16_f32 v216, v222, v223
	v_add_f32_e32 v164, v223, v164
	s_waitcnt lgkmcnt(3)
	v_mfma_f32_32x32x16_bf16 v[50:65], v[198:201], v[130:133], v[50:65]
	ds_read_b128 v[194:197], v228 offset:40448
	v_exp_f32_e32 v224, v104
	v_exp_f32_e32 v225, v105
	v_add_f32_e32 v164, v224, v164
	v_cvt_pk_bf16_f32 v217, v224, v225
	v_add_f32_e32 v164, v225, v164
	s_waitcnt lgkmcnt(3)
	v_mfma_f32_32x32x16_bf16 v[34:49], v[182:185], v[134:137], v[34:49]
	ds_read_b128 v[198:201], v228 offset:35872
	v_exp_f32_e32 v222, v106
	v_exp_f32_e32 v223, v107
	v_add_f32_e32 v164, v222, v164
	v_cvt_pk_bf16_f32 v218, v222, v223
	v_add_f32_e32 v164, v223, v164
	s_waitcnt lgkmcnt(3)
	v_mfma_f32_32x32x16_bf16 v[50:65], v[186:189], v[134:137], v[50:65]
	ds_read_b128 v[182:185], v228 offset:40480
	v_exp_f32_e32 v224, v108
	v_exp_f32_e32 v225, v109
	v_add_f32_e32 v164, v224, v164
	v_cvt_pk_bf16_f32 v219, v224, v225
	v_add_f32_e32 v164, v225, v164
	s_waitcnt lgkmcnt(3)
	v_mfma_f32_32x32x16_bf16 v[2:17], v[190:193], v[206:209], v[2:17]
	ds_read_b128 v[186:189], v228 offset:35904
	v_exp_f32_e32 v222, v110
	v_exp_f32_e32 v223, v111
	v_add_f32_e32 v164, v222, v164
	v_cvt_pk_bf16_f32 v220, v222, v223
	v_add_f32_e32 v164, v223, v164
	s_waitcnt lgkmcnt(3)
	v_mfma_f32_32x32x16_bf16 v[18:33], v[194:197], v[206:209], v[18:33]
	ds_read_b128 v[190:193], v228 offset:40512
	v_exp_f32_e32 v224, v112
	v_exp_f32_e32 v225, v113
	v_add_f32_e32 v164, v224, v164
	v_cvt_pk_bf16_f32 v221, v224, v225
	v_add_f32_e32 v164, v225, v164
	s_waitcnt lgkmcnt(3)
	v_mfma_f32_32x32x16_bf16 v[2:17], v[198:201], v[210:213], v[2:17]
	ds_read_b128 v[194:197], v228 offset:35936
	v_max3_f32 v224, v34, v35, v36
	v_max3_f32 v225, v50, v51, v52
	v_max3_f32 v224, v224, v37, v38
	s_waitcnt lgkmcnt(3)
	v_mfma_f32_32x32x16_bf16 v[18:33], v[182:185], v[210:213], v[18:33]
	ds_read_b128 v[198:201], v228 offset:40544
	v_max3_f32 v225, v225, v53, v54
	v_max3_f32 v224, v224, v39, v40
	v_max3_f32 v225, v225, v55, v56
	s_waitcnt lgkmcnt(3)
	v_mfma_f32_32x32x16_bf16 v[2:17], v[186:189], v[214:217], v[2:17]
	v_max3_f32 v224, v224, v41, v42
	v_max3_f32 v225, v225, v57, v58
	v_max3_f32 v224, v224, v43, v44
	s_add_i32 s0, s11, 3
	s_min_u32 s0, s0, s12
	s_add_i32 s0, s0, s10
	s_cmp_ge_i32 s0, s9
	s_cselect_b32 s1, s9, 0
	s_sub_i32 s19, s0, s1
	s_add_i32 s0, s11, 2
	s_min_u32 s0, s0, s12
	s_add_i32 s0, s0, s10
	s_cmp_ge_i32 s0, s9
	s_cselect_b32 s1, s9, 0
	s_sub_i32 s13, s0, s1
	s_waitcnt lgkmcnt(2)
	v_mfma_f32_32x32x16_bf16 v[18:33], v[190:193], v[214:217], v[18:33]
	v_max3_f32 v225, v225, v59, v60
	v_max3_f32 v224, v224, v45, v46
	v_max3_f32 v225, v225, v61, v62
	s_and_b64 vcc, exec, s[2:3]
	s_cbranch_vccz .Lmla_B_w47
	s_waitcnt vmcnt(3)
	ds_write_b128 v176, v[160:163] offset:22656
	ds_write_b128 v172, v[150:153] offset:22528
	ds_write_b128 v173, v[202:205] offset:13312
	v_lshl_add_u32 v229, s19, 12, v179
	global_load_dwordx4 v[160:163], v229, s[62:63]
	v_lshl_add_u32 v229, s19, 17, v178
	global_load_dwordx4 v[150:153], v229, s[52:53]
	v_lshl_add_u32 v229, s13, 7, v168
	global_load_dwordx4 v[202:205], v229, s[56:57]
	s_branch .Lmla_B_join
; #define STOREK(buf) do { LAS unsigned char* kb_ = lds + (buf) * ABUF; *(LAS u32x4*)(kb_ + (tid >> 3) * KP + (tid & 7) * 16) = kreg; \
;         if (VAR == 0 && tid < 256) *(LAS u32x4*)(kb_ + (tid >> 2) * KP + 128 + (tid & 3) * 16) = pereg; } while (0)
; #define STOREV(buf) do { *(LAS u32x4*)(lds + (buf) * ABUF + KT_BYTES + (tid >> 3) * VP + (tid & 7) * 16) = vreg; } while (0)
; template <int VAR>
; __device__ __forceinline__ void attn_phase(LAS unsigned char* lds, const AttnP P, int vcu, int G, int wave_s) {
;     ...
;             if (need_c && __any(rmc > THR)) {
;                 const float dl = __builtin_fmaxf(rmc, 0.f), f = __builtin_amdgcn_exp2f(-dl);
;                 mref += dl; lrun *= f;
; #pragma unroll
;                 for (int r = 0; r < 16; ++r) { if (USE_NEGM) { pc0[r] -= dl; pc1[r] -= dl; negm[r] = -mref; } o0[r] *= f; o1[r] *= f; }
;             }
;     ...
;             if (hn) { STOREK(t & 1); STOREV((t + 1) & 1); }
;             __syncthreads();
;             pc0 = pn0; pc1 = pn1; rmc = rmn; need_c = need_n;
.Lmla_B_w47:
	s_waitcnt vmcnt(2)
	ds_write_b128 v172, v[150:153] offset:22528
	ds_write_b128 v173, v[202:205] offset:13312
	v_lshl_add_u32 v229, s19, 17, v178
	global_load_dwordx4 v[150:153], v229, s[52:53]
	v_lshl_add_u32 v229, s13, 7, v168
	global_load_dwordx4 v[202:205], v229, s[56:57]
.Lmla_B_join:
	s_waitcnt lgkmcnt(3)
	v_mfma_f32_32x32x16_bf16 v[2:17], v[194:197], v[218:221], v[2:17]
	v_max3_f32 v224, v224, v47, v48
	v_max3_f32 v225, v225, v63, v64
	s_waitcnt lgkmcnt(2)
	v_mfma_f32_32x32x16_bf16 v[18:33], v[198:201], v[218:221], v[18:33]
	v_max3_f32 v224, v224, v49, v65
	v_max_f32_e32 v224, v224, v225
	v_mov_b32_e32 v225, v224
	v_add_f32_e32 v1, v1, v164
	s_add_i32 s11, s11, 1
	s_nop 0
	v_permlane32_swap_b32_e32 v224, v225
	s_cmp_eq_u32 s9, s11
	v_max_f32_e32 v167, v224, v225
	s_waitcnt lgkmcnt(0)
	s_barrier
	s_cbranch_scc1 .Lmla_exit_B
	s_branch .Lmla_A
.Lmla_exit_A:
	v_mov_b64_e32 v[34:35], v[82:83]
	v_mov_b64_e32 v[36:37], v[84:85]
	v_mov_b64_e32 v[38:39], v[86:87]
	v_mov_b64_e32 v[40:41], v[88:89]
	v_mov_b64_e32 v[42:43], v[90:91]
	v_mov_b64_e32 v[44:45], v[92:93]
	v_mov_b64_e32 v[46:47], v[94:95]
	v_mov_b64_e32 v[48:49], v[96:97]
	v_mov_b64_e32 v[50:51], v[98:99]
	v_mov_b64_e32 v[52:53], v[100:101]
	v_mov_b64_e32 v[54:55], v[102:103]
	v_mov_b64_e32 v[56:57], v[104:105]
	v_mov_b64_e32 v[58:59], v[106:107]
	v_mov_b64_e32 v[60:61], v[108:109]
	v_mov_b64_e32 v[62:63], v[110:111]
	v_mov_b64_e32 v[64:65], v[112:113]
	v_mov_b32_e32 v82, v167
	s_mov_b32 s11, 0x5800
	s_waitcnt vmcnt(0)
	s_branch .LBB0_1185
.Lmla_exit_B:
	v_mov_b32_e32 v82, v167
	s_mov_b32 s11, 0
	s_waitcnt vmcnt(0)
	s_branch .LBB0_1185
.Lmla_A_resc:
	v_max_f32_e32 v224, v167, v167
	v_max_f32_e32 v224, 0, v224
	v_exp_f32_e64 v225, -v224
	v_add_f32_e32 v180, v180, v224
	v_sub_f32_e32 v34, v34, v224
	v_sub_f32_e32 v35, v35, v224
	v_sub_f32_e32 v36, v36, v224
	v_sub_f32_e32 v37, v37, v224
	v_sub_f32_e32 v38, v38, v224
	v_sub_f32_e32 v39, v39, v224
	v_sub_f32_e32 v40, v40, v224
	v_sub_f32_e32 v41, v41, v224
	v_sub_f32_e32 v42, v42, v224
	v_sub_f32_e32 v43, v43, v224
	v_sub_f32_e32 v44, v44, v224
	v_sub_f32_e32 v45, v45, v224
	v_sub_f32_e32 v46, v46, v224
	v_sub_f32_e32 v47, v47, v224
	v_sub_f32_e32 v48, v48, v224
	v_sub_f32_e32 v49, v49, v224
	v_sub_f32_e32 v50, v50, v224
	v_sub_f32_e32 v51, v51, v224
	v_sub_f32_e32 v52, v52, v224
	v_sub_f32_e32 v53, v53, v224
	v_sub_f32_e32 v54, v54, v224
	v_sub_f32_e32 v55, v55, v224
	v_sub_f32_e32 v56, v56, v224
	v_sub_f32_e32 v57, v57, v224
	v_sub_f32_e32 v58, v58, v224
	v_sub_f32_e32 v59, v59, v224
	v_sub_f32_e32 v60, v60, v224
	v_sub_f32_e32 v61, v61, v224
	v_sub_f32_e32 v62, v62, v224
	v_sub_f32_e32 v63, v63, v224
	v_sub_f32_e32 v64, v64, v224
	v_sub_f32_e32 v65, v65, v224
	v_mul_f32_e32 v2, v2, v225
	v_mul_f32_e32 v3, v3, v225
	v_mul_f32_e32 v4, v4, v225
	v_mul_f32_e32 v5, v5, v225
	v_mul_f32_e32 v6, v6, v225
	v_mul_f32_e32 v7, v7, v225
	v_mul_f32_e32 v8, v8, v225
	v_mul_f32_e32 v9, v9, v225
	v_mul_f32_e32 v10, v10, v225
	v_mul_f32_e32 v11, v11, v225
	v_mul_f32_e32 v12, v12, v225
	v_mul_f32_e32 v13, v13, v225
	v_mul_f32_e32 v14, v14, v225
	v_mul_f32_e32 v15, v15, v225
	v_mul_f32_e32 v16, v16, v225
	v_mul_f32_e32 v17, v17, v225
	v_mul_f32_e32 v18, v18, v225
	v_mul_f32_e32 v19, v19, v225
	v_mul_f32_e32 v20, v20, v225
	v_mul_f32_e32 v21, v21, v225
	v_mul_f32_e32 v22, v22, v225
	v_mul_f32_e32 v23, v23, v225
	v_mul_f32_e32 v24, v24, v225
	v_mul_f32_e32 v25, v25, v225
	v_mul_f32_e32 v26, v26, v225
	v_mul_f32_e32 v27, v27, v225
	v_mul_f32_e32 v28, v28, v225
	v_mul_f32_e32 v29, v29, v225
	v_mul_f32_e32 v30, v30, v225
	v_mul_f32_e32 v31, v31, v225
	v_mul_f32_e32 v32, v32, v225
	v_mul_f32_e32 v33, v33, v225
	v_mul_f32_e32 v1, v1, v225
	v_xor_b32_e32 v66, 0x80000000, v180
	v_mov_b32_e32 v67, v66
	v_mov_b32_e32 v68, v66
	v_mov_b32_e32 v69, v66
	v_mov_b32_e32 v70, v66
	v_mov_b32_e32 v71, v66
	v_mov_b32_e32 v72, v66
	v_mov_b32_e32 v73, v66
	v_mov_b32_e32 v74, v66
	v_mov_b32_e32 v75, v66
	v_mov_b32_e32 v76, v66
	v_mov_b32_e32 v77, v66
	v_mov_b32_e32 v78, v66
	v_mov_b32_e32 v79, v66
	v_mov_b32_e32 v80, v66
	v_mov_b32_e32 v81, v66
	s_branch .Lmla_A_go
.Lmla_B_resc:
	v_max_f32_e32 v224, v167, v167
	v_max_f32_e32 v224, 0, v224
	v_exp_f32_e64 v225, -v224
	v_add_f32_e32 v180, v180, v224
	v_sub_f32_e32 v82, v82, v224
	v_sub_f32_e32 v83, v83, v224
	v_sub_f32_e32 v84, v84, v224
	v_sub_f32_e32 v85, v85, v224
	v_sub_f32_e32 v86, v86, v224
	v_sub_f32_e32 v87, v87, v224
	v_sub_f32_e32 v88, v88, v224
	v_sub_f32_e32 v89, v89, v224
	v_sub_f32_e32 v90, v90, v224
	v_sub_f32_e32 v91, v91, v224
	v_sub_f32_e32 v92, v92, v224
	v_sub_f32_e32 v93, v93, v224
	v_sub_f32_e32 v94, v94, v224
	v_sub_f32_e32 v95, v95, v224
	v_sub_f32_e32 v96, v96, v224
	v_sub_f32_e32 v97, v97, v224
	v_sub_f32_e32 v98, v98, v224
	v_sub_f32_e32 v99, v99, v224
	v_sub_f32_e32 v100, v100, v224
	v_sub_f32_e32 v101, v101, v224
	v_sub_f32_e32 v102, v102, v224
	v_sub_f32_e32 v103, v103, v224
	v_sub_f32_e32 v104, v104, v224
	v_sub_f32_e32 v105, v105, v224
	v_sub_f32_e32 v106, v106, v224
	v_sub_f32_e32 v107, v107, v224
	v_sub_f32_e32 v108, v108, v224
	v_sub_f32_e32 v109, v109, v224
	v_sub_f32_e32 v110, v110, v224
	v_sub_f32_e32 v111, v111, v224
	v_sub_f32_e32 v112, v112, v224
	v_sub_f32_e32 v113, v113, v224
	v_mul_f32_e32 v2, v2, v225
	v_mul_f32_e32 v3, v3, v225
	v_mul_f32_e32 v4, v4, v225
	v_mul_f32_e32 v5, v5, v225
	v_mul_f32_e32 v6, v6, v225
	v_mul_f32_e32 v7, v7, v225
	v_mul_f32_e32 v8, v8, v225
	v_mul_f32_e32 v9, v9, v225
	v_mul_f32_e32 v10, v10, v225
	v_mul_f32_e32 v11, v11, v225
	v_mul_f32_e32 v12, v12, v225
	v_mul_f32_e32 v13, v13, v225
	v_mul_f32_e32 v14, v14, v225
	v_mul_f32_e32 v15, v15, v225
	v_mul_f32_e32 v16, v16, v225
	v_mul_f32_e32 v17, v17, v225
	v_mul_f32_e32 v18, v18, v225
	v_mul_f32_e32 v19, v19, v225
	v_mul_f32_e32 v20, v20, v225
	v_mul_f32_e32 v21, v21, v225
	v_mul_f32_e32 v22, v22, v225
	v_mul_f32_e32 v23, v23, v225
	v_mul_f32_e32 v24, v24, v225
	v_mul_f32_e32 v25, v25, v225
	v_mul_f32_e32 v26, v26, v225
	v_mul_f32_e32 v27, v27, v225
	v_mul_f32_e32 v28, v28, v225
	v_mul_f32_e32 v29, v29, v225
	v_mul_f32_e32 v30, v30, v225
	v_mul_f32_e32 v31, v31, v225
	v_mul_f32_e32 v32, v32, v225
	v_mul_f32_e32 v33, v33, v225
	v_mul_f32_e32 v1, v1, v225
	v_xor_b32_e32 v66, 0x80000000, v180
	v_mov_b32_e32 v67, v66
	v_mov_b32_e32 v68, v66
	v_mov_b32_e32 v69, v66
	v_mov_b32_e32 v70, v66
	v_mov_b32_e32 v71, v66
	v_mov_b32_e32 v72, v66
	v_mov_b32_e32 v73, v66
	v_mov_b32_e32 v74, v66
	v_mov_b32_e32 v75, v66
	v_mov_b32_e32 v76, v66
	v_mov_b32_e32 v77, v66
	v_mov_b32_e32 v78, v66
	v_mov_b32_e32 v79, v66
	v_mov_b32_e32 v80, v66
	v_mov_b32_e32 v81, v66
	s_branch .Lmla_B_go
